# down epilogue: last block's two residual loads issued early into already-consumed prefetch registers (counted vmcnt(12)) instead of load+vmcnt(0) store drains
# baseline (speedup 1.0000x reference)
; #define G8_STAGE(bufoff, gbase) do { _Pragma("unroll") for (int _i = 0; _i < 2; ++_i) \
;     __builtin_amdgcn_global_load_lds((const unsigned*)((const char*)(gbase) + voffA[_i]), (LAS unsigned*)(lds + (bufoff) + ldsw + _i * 8192), 16, 0, 0); } while (0)
; #define G8_LDA(dst, b, h) do { _Pragma("unroll") for (int m = 0; m < 4; ++m) _Pragma("unroll") for (int k = 0; k < 2; ++k) dst[m][k] = *(const LAS h16x8*)(lds + G8_SA(b, h) + aoff + m * 2048 + k * 1024); } while (0)
; #define G8_LDB(dst, b, h) do { _Pragma("unroll") for (int n = 0; n < 2; ++n) _Pragma("unroll") for (int k = 0; k < 2; ++k) dst[n][k] = *(const LAS h16x8*)(lds + G8_SB(b, h) + boff + n * 2048 + k * 1024); } while (0)
; #define G8_MMA(ai, bj, At, Bt_) do { __builtin_amdgcn_s_setprio(1); _Pragma("unroll") for (int m = 0; m < 4; ++m) _Pragma("unroll") for (int n = 0; n < 2; ++n) _Pragma("unroll") for (int k = 0; k < 2; ++k) \
;     acc[ai][bj][m][n] = __builtin_amdgcn_mfma_f32_16x16x32_f16(Bt_[n][k], At[m][k], acc[ai][bj][m][n], 0, 0, 0); __builtin_amdgcn_s_setprio(0); } while (0)
; #define G8_WAIT_V(n) asm volatile("s_waitcnt vmcnt(" #n ")" ::: "memory")
; #define G8_WAIT_L(n) asm volatile("s_waitcnt lgkmcnt(" #n ")" ::: "memory")
; #define G8_BAR __builtin_amdgcn_s_barrier()
; #define G8_SCHED __builtin_amdgcn_sched_barrier(0)
; template <class Epi>
; __device__ __forceinline__ void gemm_phase(LAS unsigned char* lds, const h16* A, const h16* Bt, int K, const Order& S, const Epi& E) {
;     ...
;       G8_LDB(B0, 0, 0); G8_SCHED; G8_LDA(At, 0, 0); G8_STAGE(G8_SA(1, 1), a1 + hstep);
;       G8_WAIT_L(8); G8_BAR; G8_WAIT_L(0); G8_MMA(0, 0, At, B0); G8_BAR; G8_SCHED;
;       G8_LDB(B1, 0, 1); G8_STAGE(G8_SB(0, 0), b2);
;       G8_BAR; G8_WAIT_L(0); G8_MMA(0, 1, At, B1); G8_BAR;
;       G8_LDA(At, 0, 1); G8_STAGE(G8_SA(0, 0), a2);
;       G8_BAR; G8_WAIT_L(0); G8_MMA(1, 0, At, B0); G8_BAR; G8_SCHED;
;       G8_STAGE(G8_SB(0, 1), b2 + hstep);
;       G8_WAIT_V(6); G8_BAR; G8_MMA(1, 1, At, B1); G8_BAR;
.LBB0_2542:
	v_or_b32_e32 v140, 0x10000, v158
	v_add_u32_e32 v141, 0x10400, v158
	ds_read_b128 v[152:155], v140
	ds_read_b128 v[160:163], v141
	v_add_u32_e32 v140, 0x10800, v158
	v_add_u32_e32 v141, 0x10c00, v158
	ds_read_b128 v[164:167], v140
	ds_read_b128 v[168:171], v141
	s_add_u32 s24, s22, 0xfff00080
	s_addc_u32 s25, s23, -1
	s_cmp_eq_u32 s53, 60
	s_cselect_b32 s27, s3, s25
	s_cselect_b32 s26, s9, s24
	s_cselect_b32 s25, s15, s52
	s_cselect_b32 s24, s17, s51
	v_lshl_add_u64 v[140:141], s[22:23], 0, v[136:137]
	s_add_i32 m0, s35, 0xc000
	ds_read_b128 v[172:175], v135
	ds_read_b128 v[176:179], v135 offset:1024
	ds_read_b128 v[180:183], v135 offset:2048
	ds_read_b128 v[184:187], v135 offset:3072
	ds_read_b128 v[202:205], v135 offset:4096
	ds_read_b128 v[206:209], v135 offset:5120
	ds_read_b128 v[210:213], v135 offset:6144
	ds_read_b128 v[214:217], v135 offset:7168
	global_load_lds_dwordx4 v[140:141], off
	v_lshl_add_u64 v[140:141], s[22:23], 0, v[138:139]
	s_add_i32 m0, s35, 0xe000
	s_nop 0
	global_load_lds_dwordx4 v[140:141], off
	s_waitcnt lgkmcnt(8)
	s_barrier
	s_waitcnt lgkmcnt(0)
	s_setprio 1
	s_waitcnt lgkmcnt(0)
	v_mfma_f32_16x16x32_f16 v[126:129], v[152:155], v[172:175], v[126:129]
	v_mfma_f32_16x16x32_f16 v[122:125], v[164:167], v[172:175], v[122:125]
	v_mfma_f32_16x16x32_f16 v[110:113], v[152:155], v[180:183], v[110:113]
	v_mfma_f32_16x16x32_f16 v[106:109], v[164:167], v[180:183], v[106:109]
	v_mfma_f32_16x16x32_f16 v[94:97], v[152:155], v[202:205], v[94:97]
	v_mfma_f32_16x16x32_f16 v[90:93], v[164:167], v[202:205], v[90:93]
	v_mfma_f32_16x16x32_f16 v[78:81], v[152:155], v[210:213], v[78:81]
	v_mfma_f32_16x16x32_f16 v[74:77], v[164:167], v[210:213], v[74:77]
	v_mfma_f32_16x16x32_f16 v[126:129], v[160:163], v[176:179], v[126:129]
	v_mfma_f32_16x16x32_f16 v[122:125], v[168:171], v[176:179], v[122:125]
	v_mfma_f32_16x16x32_f16 v[110:113], v[160:163], v[184:187], v[110:113]
	v_mfma_f32_16x16x32_f16 v[106:109], v[168:171], v[184:187], v[106:109]
	v_mfma_f32_16x16x32_f16 v[94:97], v[160:163], v[206:209], v[94:97]
	v_mfma_f32_16x16x32_f16 v[90:93], v[168:171], v[206:209], v[90:93]
	v_mfma_f32_16x16x32_f16 v[78:81], v[160:163], v[214:217], v[78:81]
	v_mfma_f32_16x16x32_f16 v[74:77], v[168:171], v[214:217], v[74:77]
	s_setprio 0
	s_barrier
	v_or_b32_e32 v140, 0x14000, v158
	v_add_u32_e32 v141, 0x14400, v158
	ds_read_b128 v[218:221], v140
	ds_read_b128 v[222:225], v141
	v_add_u32_e32 v140, 0x14800, v158
	v_add_u32_e32 v141, 0x14c00, v158
	s_mov_b32 m0, s36
	ds_read_b128 v[226:229], v140
	ds_read_b128 v[230:233], v141
	v_lshl_add_u64 v[140:141], s[24:25], 0, v[0:1]
	global_load_lds_dwordx4 v[140:141], off
	v_lshl_add_u64 v[156:157], s[24:25], 0, v[130:131]
	s_mov_b32 m0, s37
	s_nop 0
	global_load_lds_dwordx4 v[156:157], off
	s_barrier
	s_waitcnt lgkmcnt(0)
	s_setprio 1
	s_waitcnt lgkmcnt(0)
	v_mfma_f32_16x16x32_f16 v[118:121], v[218:221], v[172:175], v[118:121]
	v_mfma_f32_16x16x32_f16 v[114:117], v[226:229], v[172:175], v[114:117]
	v_mfma_f32_16x16x32_f16 v[102:105], v[218:221], v[180:183], v[102:105]
	v_mfma_f32_16x16x32_f16 v[98:101], v[226:229], v[180:183], v[98:101]
	v_mfma_f32_16x16x32_f16 v[86:89], v[218:221], v[202:205], v[86:89]
	v_mfma_f32_16x16x32_f16 v[82:85], v[226:229], v[202:205], v[82:85]
	v_mfma_f32_16x16x32_f16 v[70:73], v[218:221], v[210:213], v[70:73]
	v_mfma_f32_16x16x32_f16 v[66:69], v[226:229], v[210:213], v[66:69]
	v_mfma_f32_16x16x32_f16 v[118:121], v[222:225], v[176:179], v[118:121]
	v_mfma_f32_16x16x32_f16 v[114:117], v[230:233], v[176:179], v[114:117]
	v_mfma_f32_16x16x32_f16 v[102:105], v[222:225], v[184:187], v[102:105]
	v_mfma_f32_16x16x32_f16 v[98:101], v[230:233], v[184:187], v[98:101]
	v_mfma_f32_16x16x32_f16 v[86:89], v[222:225], v[206:209], v[86:89]
	v_mfma_f32_16x16x32_f16 v[82:85], v[230:233], v[206:209], v[82:85]
	v_mfma_f32_16x16x32_f16 v[70:73], v[222:225], v[214:217], v[70:73]
	v_mfma_f32_16x16x32_f16 v[66:69], v[230:233], v[214:217], v[66:69]
	s_setprio 0
	s_mov_b32 m0, s35
	v_lshl_add_u64 v[188:189], s[26:27], 0, v[0:1]
	s_barrier
	ds_read_b128 v[172:175], v135 offset:16384
	ds_read_b128 v[176:179], v135 offset:17408
	ds_read_b128 v[180:183], v135 offset:18432
	ds_read_b128 v[184:187], v135 offset:19456
	ds_read_b128 v[202:205], v135 offset:20480
	ds_read_b128 v[206:209], v135 offset:21504
	ds_read_b128 v[210:213], v135 offset:22528
	ds_read_b128 v[214:217], v135 offset:23552
	global_load_lds_dwordx4 v[188:189], off
	v_lshl_add_u64 v[234:235], s[26:27], 0, v[130:131]
	s_mov_b32 m0, s38
	s_nop 0
	global_load_lds_dwordx4 v[234:235], off
	s_barrier
	s_waitcnt lgkmcnt(0)
	s_setprio 1
	s_waitcnt lgkmcnt(0)
	v_mfma_f32_16x16x32_f16 v[62:65], v[152:155], v[172:175], v[62:65]
	v_mfma_f32_16x16x32_f16 v[58:61], v[164:167], v[172:175], v[58:61]
	v_mfma_f32_16x16x32_f16 v[46:49], v[152:155], v[180:183], v[46:49]
	v_mfma_f32_16x16x32_f16 v[42:45], v[164:167], v[180:183], v[42:45]
	v_mfma_f32_16x16x32_f16 v[30:33], v[152:155], v[202:205], v[30:33]
	v_mfma_f32_16x16x32_f16 v[26:29], v[164:167], v[202:205], v[26:29]
	v_mfma_f32_16x16x32_f16 v[14:17], v[152:155], v[210:213], v[14:17]
	v_mfma_f32_16x16x32_f16 v[10:13], v[164:167], v[210:213], v[10:13]
	v_mfma_f32_16x16x32_f16 v[62:65], v[160:163], v[176:179], v[62:65]
	v_mfma_f32_16x16x32_f16 v[58:61], v[168:171], v[176:179], v[58:61]
	v_mfma_f32_16x16x32_f16 v[46:49], v[160:163], v[184:187], v[46:49]
	v_mfma_f32_16x16x32_f16 v[42:45], v[168:171], v[184:187], v[42:45]
	v_mfma_f32_16x16x32_f16 v[30:33], v[160:163], v[206:209], v[30:33]
	v_mfma_f32_16x16x32_f16 v[26:29], v[168:171], v[206:209], v[26:29]
	v_mfma_f32_16x16x32_f16 v[14:17], v[160:163], v[214:217], v[14:17]
	v_mfma_f32_16x16x32_f16 v[10:13], v[168:171], v[214:217], v[10:13]
	s_setprio 0
	s_barrier
; #define G8_STAGE(bufoff, gbase) do { _Pragma("unroll") for (int _i = 0; _i < 2; ++_i) \
;     __builtin_amdgcn_global_load_lds((const unsigned*)((const char*)(gbase) + voffA[_i]), (LAS unsigned*)(lds + (bufoff) + ldsw + _i * 8192), 16, 0, 0); } while (0)
; #define G8_LDA(dst, b, h) do { _Pragma("unroll") for (int m = 0; m < 4; ++m) _Pragma("unroll") for (int k = 0; k < 2; ++k) dst[m][k] = *(const LAS h16x8*)(lds + G8_SA(b, h) + aoff + m * 2048 + k * 1024); } while (0)
; #define G8_LDB(dst, b, h) do { _Pragma("unroll") for (int n = 0; n < 2; ++n) _Pragma("unroll") for (int k = 0; k < 2; ++k) dst[n][k] = *(const LAS h16x8*)(lds + G8_SB(b, h) + boff + n * 2048 + k * 1024); } while (0)
; #define G8_MMA(ai, bj, At, Bt_) do { __builtin_amdgcn_s_setprio(1); _Pragma("unroll") for (int m = 0; m < 4; ++m) _Pragma("unroll") for (int n = 0; n < 2; ++n) _Pragma("unroll") for (int k = 0; k < 2; ++k) \
;     acc[ai][bj][m][n] = __builtin_amdgcn_mfma_f32_16x16x32_f16(Bt_[n][k], At[m][k], acc[ai][bj][m][n], 0, 0, 0); __builtin_amdgcn_s_setprio(0); } while (0)
; #define G8_WAIT_V(n) asm volatile("s_waitcnt vmcnt(" #n ")" ::: "memory")
; #define G8_WAIT_L(n) asm volatile("s_waitcnt lgkmcnt(" #n ")" ::: "memory")
; #define G8_BAR __builtin_amdgcn_s_barrier()
; #define G8_SCHED __builtin_amdgcn_sched_barrier(0)
; template <class Epi>
; __device__ __forceinline__ void gemm_phase(LAS unsigned char* lds, const h16* A, const h16* Bt, int K, const Order& S, const Epi& E) {
;     ...
;       G8_WAIT_V(6); G8_BAR; G8_MMA(1, 1, At, B1); G8_BAR;
;       G8_LDB(B0, 1, 0); G8_SCHED; G8_LDA(At, 1, 0); G8_STAGE(G8_SA(0, 1), a2 + hstep);
;       G8_WAIT_L(8); G8_BAR; G8_WAIT_L(0); G8_MMA(0, 0, At, B0); G8_BAR; G8_SCHED;
;       G8_LDB(B1, 1, 1); G8_STAGE(G8_SB(1, 0), b3);
;       G8_BAR; G8_WAIT_L(0); G8_MMA(0, 1, At, B1); G8_BAR;
;       G8_LDA(At, 1, 1); G8_STAGE(G8_SA(1, 0), a3);
;       G8_BAR; G8_WAIT_L(0); G8_MMA(1, 0, At, B0); G8_BAR; G8_SCHED;
	s_add_u32 s54, s24, 0x100000
	s_addc_u32 s55, s25, 0
	s_mov_b32 m0, s39
	v_lshl_add_u64 v[152:153], s[54:55], 0, v[0:1]
	global_load_lds_dwordx4 v[152:153], off
	v_lshl_add_u64 v[152:153], s[54:55], 0, v[130:131]
	s_mov_b32 m0, s40
	s_nop 0
	global_load_lds_dwordx4 v[152:153], off
	s_waitcnt vmcnt(6)
	s_barrier
	s_setprio 1
	v_mfma_f32_16x16x32_f16 v[54:57], v[218:221], v[172:175], v[54:57]
	v_mfma_f32_16x16x32_f16 v[50:53], v[226:229], v[172:175], v[50:53]
	v_mfma_f32_16x16x32_f16 v[38:41], v[218:221], v[180:183], v[38:41]
	v_mfma_f32_16x16x32_f16 v[34:37], v[226:229], v[180:183], v[34:37]
	v_mfma_f32_16x16x32_f16 v[22:25], v[218:221], v[202:205], v[22:25]
	v_mfma_f32_16x16x32_f16 v[18:21], v[226:229], v[202:205], v[18:21]
	v_mfma_f32_16x16x32_f16 v[6:9], v[218:221], v[210:213], v[6:9]
	v_mfma_f32_16x16x32_f16 v[2:5], v[226:229], v[210:213], v[2:5]
	v_mfma_f32_16x16x32_f16 v[54:57], v[222:225], v[176:179], v[54:57]
	v_mfma_f32_16x16x32_f16 v[50:53], v[230:233], v[176:179], v[50:53]
	v_mfma_f32_16x16x32_f16 v[38:41], v[222:225], v[184:187], v[38:41]
	v_mfma_f32_16x16x32_f16 v[34:37], v[230:233], v[184:187], v[34:37]
	v_mfma_f32_16x16x32_f16 v[22:25], v[222:225], v[206:209], v[22:25]
	v_mfma_f32_16x16x32_f16 v[18:21], v[230:233], v[206:209], v[18:21]
	v_mfma_f32_16x16x32_f16 v[6:9], v[222:225], v[214:217], v[6:9]
	v_mfma_f32_16x16x32_f16 v[2:5], v[230:233], v[214:217], v[2:5]
	s_setprio 0
	v_or_b32_e32 v152, 0x18000, v158
	v_add_u32_e32 v159, 0x18400, v158
	s_barrier
	ds_read_b128 v[152:155], v152
	ds_read_b128 v[160:163], v159
	v_add_u32_e32 v159, 0x18800, v158
	v_add_u32_e32 v168, 0x18c00, v158
	ds_read_b128 v[164:167], v159
	ds_read_b128 v[168:171], v168
	s_add_u32 s26, s26, 0x100000
	s_addc_u32 s27, s27, 0
	s_mov_b32 m0, s41
	v_lshl_add_u64 v[218:219], s[26:27], 0, v[0:1]
	ds_read_b128 v[172:175], v135 offset:32768
	ds_read_b128 v[176:179], v135 offset:33792
	ds_read_b128 v[180:183], v135 offset:34816
	ds_read_b128 v[184:187], v135 offset:35840
	ds_read_b128 v[202:205], v135 offset:36864
	ds_read_b128 v[206:209], v135 offset:37888
	ds_read_b128 v[210:213], v135 offset:38912
	ds_read_b128 v[214:217], v135 offset:39936
	global_load_lds_dwordx4 v[218:219], off
	v_lshl_add_u64 v[218:219], s[26:27], 0, v[130:131]
	s_mov_b32 m0, s42
	s_nop 0
	global_load_lds_dwordx4 v[218:219], off
	s_waitcnt lgkmcnt(8)
	s_barrier
	s_waitcnt lgkmcnt(0)
	s_setprio 1
	s_waitcnt lgkmcnt(0)
	v_mfma_f32_16x16x32_f16 v[126:129], v[152:155], v[172:175], v[126:129]
	v_mfma_f32_16x16x32_f16 v[122:125], v[164:167], v[172:175], v[122:125]
	v_mfma_f32_16x16x32_f16 v[110:113], v[152:155], v[180:183], v[110:113]
	v_mfma_f32_16x16x32_f16 v[106:109], v[164:167], v[180:183], v[106:109]
	v_mfma_f32_16x16x32_f16 v[94:97], v[152:155], v[202:205], v[94:97]
	v_mfma_f32_16x16x32_f16 v[90:93], v[164:167], v[202:205], v[90:93]
	v_mfma_f32_16x16x32_f16 v[78:81], v[152:155], v[210:213], v[78:81]
	v_mfma_f32_16x16x32_f16 v[74:77], v[164:167], v[210:213], v[74:77]
	v_mfma_f32_16x16x32_f16 v[126:129], v[160:163], v[176:179], v[126:129]
	v_mfma_f32_16x16x32_f16 v[122:125], v[168:171], v[176:179], v[122:125]
	v_mfma_f32_16x16x32_f16 v[110:113], v[160:163], v[184:187], v[110:113]
	v_mfma_f32_16x16x32_f16 v[106:109], v[168:171], v[184:187], v[106:109]
	v_mfma_f32_16x16x32_f16 v[94:97], v[160:163], v[206:209], v[94:97]
	v_mfma_f32_16x16x32_f16 v[90:93], v[168:171], v[206:209], v[90:93]
	v_mfma_f32_16x16x32_f16 v[78:81], v[160:163], v[214:217], v[78:81]
	v_mfma_f32_16x16x32_f16 v[74:77], v[168:171], v[214:217], v[74:77]
	s_setprio 0
	s_barrier
	v_or_b32_e32 v159, 0x1c000, v158
	s_mov_b32 m0, s44
	v_add_u32_e32 v195, 0x1c400, v158
	ds_read_b128 v[218:221], v159
	ds_read_b128 v[222:225], v195
	v_add_u32_e32 v159, 0x1c800, v158
	v_lshl_add_u64 v[140:141], v[140:141], 0, s[94:95]
	v_add_u32_e32 v195, 0x1cc00, v158
	ds_read_b128 v[226:229], v159
	ds_read_b128 v[230:233], v195
	global_load_lds_dwordx4 v[140:141], off
	v_lshl_add_u64 v[140:141], v[156:157], 0, s[94:95]
	s_mov_b32 m0, s45
	s_nop 0
	global_load_lds_dwordx4 v[140:141], off
	s_barrier
	s_waitcnt lgkmcnt(0)
	s_setprio 1
	s_waitcnt lgkmcnt(0)
	v_mfma_f32_16x16x32_f16 v[118:121], v[218:221], v[172:175], v[118:121]
	v_mfma_f32_16x16x32_f16 v[114:117], v[226:229], v[172:175], v[114:117]
	v_mfma_f32_16x16x32_f16 v[102:105], v[218:221], v[180:183], v[102:105]
	v_mfma_f32_16x16x32_f16 v[98:101], v[226:229], v[180:183], v[98:101]
	v_mfma_f32_16x16x32_f16 v[86:89], v[218:221], v[202:205], v[86:89]
	v_mfma_f32_16x16x32_f16 v[82:85], v[226:229], v[202:205], v[82:85]
	v_mfma_f32_16x16x32_f16 v[70:73], v[218:221], v[210:213], v[70:73]
	v_mfma_f32_16x16x32_f16 v[66:69], v[226:229], v[210:213], v[66:69]
	v_mfma_f32_16x16x32_f16 v[118:121], v[222:225], v[176:179], v[118:121]
	v_mfma_f32_16x16x32_f16 v[114:117], v[230:233], v[176:179], v[114:117]
	v_mfma_f32_16x16x32_f16 v[102:105], v[222:225], v[184:187], v[102:105]
	v_mfma_f32_16x16x32_f16 v[98:101], v[230:233], v[184:187], v[98:101]
	v_mfma_f32_16x16x32_f16 v[86:89], v[222:225], v[206:209], v[86:89]
	v_mfma_f32_16x16x32_f16 v[82:85], v[230:233], v[206:209], v[82:85]
	v_mfma_f32_16x16x32_f16 v[70:73], v[222:225], v[214:217], v[70:73]
	v_mfma_f32_16x16x32_f16 v[66:69], v[230:233], v[214:217], v[66:69]
	s_setprio 0
	s_mov_b32 m0, s46
	v_lshl_add_u64 v[140:141], v[188:189], 0, s[94:95]
	s_barrier
	ds_read_b128 v[172:175], v135 offset:49152
	ds_read_b128 v[176:179], v135 offset:50176
	ds_read_b128 v[180:183], v135 offset:51200
	ds_read_b128 v[184:187], v135 offset:52224
	ds_read_b128 v[202:205], v135 offset:53248
	ds_read_b128 v[206:209], v135 offset:54272
	ds_read_b128 v[210:213], v135 offset:55296
	ds_read_b128 v[214:217], v135 offset:56320
	global_load_lds_dwordx4 v[140:141], off
	v_lshl_add_u64 v[140:141], v[234:235], 0, s[94:95]
	s_mov_b32 m0, s47
	s_nop 0
	global_load_lds_dwordx4 v[140:141], off
	s_barrier
; #define G8_STAGE(bufoff, gbase) do { _Pragma("unroll") for (int _i = 0; _i < 2; ++_i) \
;     __builtin_amdgcn_global_load_lds((const unsigned*)((const char*)(gbase) + voffA[_i]), (LAS unsigned*)(lds + (bufoff) + ldsw + _i * 8192), 16, 0, 0); } while (0)
; #define G8_MMA(ai, bj, At, Bt_) do { __builtin_amdgcn_s_setprio(1); _Pragma("unroll") for (int m = 0; m < 4; ++m) _Pragma("unroll") for (int n = 0; n < 2; ++n) _Pragma("unroll") for (int k = 0; k < 2; ++k) \
;     acc[ai][bj][m][n] = __builtin_amdgcn_mfma_f32_16x16x32_f16(Bt_[n][k], At[m][k], acc[ai][bj][m][n], 0, 0, 0); __builtin_amdgcn_s_setprio(0); } while (0)
; #define G8_WAIT_V(n) asm volatile("s_waitcnt vmcnt(" #n ")" ::: "memory")
; #define G8_WAIT_L(n) asm volatile("s_waitcnt lgkmcnt(" #n ")" ::: "memory")
; #define G8_BAR __builtin_amdgcn_s_barrier()
; #define G8_SCHED __builtin_amdgcn_sched_barrier(0)
; template <class Epi>
; __device__ __forceinline__ void gemm_phase(LAS unsigned char* lds, const h16* A, const h16* Bt, int K, const Order& S, const Epi& E) {
;     ...
;       G8_BAR; G8_WAIT_L(0); G8_MMA(1, 0, At, B0); G8_BAR; G8_SCHED;
;       G8_STAGE(G8_SB(1, 1), b3 + hstep);
;       G8_WAIT_V(6); G8_BAR; G8_MMA(1, 1, At, B1); G8_BAR;
;   __device__ __forceinline__ void operator()(const f32x4 (&acc)[2][2][4][2], const g8::Unit& u, int ui, int wr, int wc, int fr, int fq) const {
; #pragma unroll
;     for (int ai = 0; ai < 2; ++ai)
; #pragma unroll
;       for (int m = 0; m < 4; ++m) {
;         const size_t row = (size_t)u.pm * 256 + 128 * ai + 64 * wr + 16 * m + fr;
;         const size_t base = row * DM + 256 * u.pn + 32 * wc + 8 * fq;
;         float ss = 0.f;
; #pragma unroll
;         for (int bj = 0; bj < 2; ++bj) {
;           const size_t idx = base + 128 * bj;
;           const h16x8 xv = *(const h16x8*)(xb + idx);
;           f32x4 x0 = acc[ai][bj][m][0], x1 = acc[ai][bj][m][1];
; #pragma unroll
;           for (int j = 0; j < 4; ++j) { x0[j] += (float)xv[j]; x1[j] += (float)xv[4 + j]; ss += x0[j] * x0[j] + x1[j] * x1[j]; }
;           if (final_out) {
;             __builtin_nontemporal_store(x0, (f32x4*)(xo + idx));
;             __builtin_nontemporal_store(x1, (f32x4*)(xo + idx + 4));
;           } else {
;             *(h16x8*)(xb + idx) = pack8(x0, x1);
;           }
	s_waitcnt lgkmcnt(0)
	s_setprio 1
	s_waitcnt lgkmcnt(0)
	v_mfma_f32_16x16x32_f16 v[62:65], v[152:155], v[172:175], v[62:65]
	v_mfma_f32_16x16x32_f16 v[58:61], v[164:167], v[172:175], v[58:61]
	v_mfma_f32_16x16x32_f16 v[46:49], v[152:155], v[180:183], v[46:49]
	v_mfma_f32_16x16x32_f16 v[42:45], v[164:167], v[180:183], v[42:45]
	v_mfma_f32_16x16x32_f16 v[30:33], v[152:155], v[202:205], v[30:33]
	v_mfma_f32_16x16x32_f16 v[26:29], v[164:167], v[202:205], v[26:29]
	v_mfma_f32_16x16x32_f16 v[14:17], v[152:155], v[210:213], v[14:17]
	v_mfma_f32_16x16x32_f16 v[10:13], v[164:167], v[210:213], v[10:13]
	v_mfma_f32_16x16x32_f16 v[62:65], v[160:163], v[176:179], v[62:65]
	v_mfma_f32_16x16x32_f16 v[58:61], v[168:171], v[176:179], v[58:61]
	v_mfma_f32_16x16x32_f16 v[46:49], v[160:163], v[184:187], v[46:49]
	v_mfma_f32_16x16x32_f16 v[42:45], v[168:171], v[184:187], v[42:45]
	v_mfma_f32_16x16x32_f16 v[30:33], v[160:163], v[206:209], v[30:33]
	v_mfma_f32_16x16x32_f16 v[26:29], v[168:171], v[206:209], v[26:29]
	v_mfma_f32_16x16x32_f16 v[14:17], v[160:163], v[214:217], v[14:17]
	v_mfma_f32_16x16x32_f16 v[10:13], v[168:171], v[214:217], v[10:13]
	s_setprio 0
	s_barrier
	s_add_u32 s24, s24, 0x100080
	s_addc_u32 s25, s25, 0
	s_mov_b32 m0, s48
	v_lshl_add_u64 v[140:141], s[24:25], 0, v[0:1]
	global_load_lds_dwordx4 v[140:141], off
	v_lshl_add_u64 v[140:141], s[24:25], 0, v[130:131]
	s_mov_b32 m0, s49
	s_nop 0
	global_load_lds_dwordx4 v[140:141], off
	s_waitcnt vmcnt(6)
	s_barrier
	s_setprio 1
	v_mfma_f32_16x16x32_f16 v[54:57], v[218:221], v[172:175], v[54:57]
	v_mfma_f32_16x16x32_f16 v[50:53], v[226:229], v[172:175], v[50:53]
	v_mfma_f32_16x16x32_f16 v[38:41], v[218:221], v[180:183], v[38:41]
	v_mfma_f32_16x16x32_f16 v[34:37], v[226:229], v[180:183], v[34:37]
	v_mfma_f32_16x16x32_f16 v[22:25], v[218:221], v[202:205], v[22:25]
	v_mfma_f32_16x16x32_f16 v[18:21], v[226:229], v[202:205], v[18:21]
	v_mfma_f32_16x16x32_f16 v[6:9], v[218:221], v[210:213], v[6:9]
	v_mfma_f32_16x16x32_f16 v[2:5], v[226:229], v[210:213], v[2:5]
	v_mfma_f32_16x16x32_f16 v[54:57], v[222:225], v[176:179], v[54:57]
	v_mfma_f32_16x16x32_f16 v[50:53], v[230:233], v[176:179], v[50:53]
	v_mfma_f32_16x16x32_f16 v[38:41], v[222:225], v[184:187], v[38:41]
	v_mfma_f32_16x16x32_f16 v[34:37], v[230:233], v[184:187], v[34:37]
	v_mfma_f32_16x16x32_f16 v[22:25], v[222:225], v[206:209], v[22:25]
	v_mfma_f32_16x16x32_f16 v[18:21], v[230:233], v[206:209], v[18:21]
	v_mfma_f32_16x16x32_f16 v[6:9], v[222:225], v[214:217], v[6:9]
	v_mfma_f32_16x16x32_f16 v[2:5], v[230:233], v[214:217], v[2:5]
	s_setprio 0
	s_add_i32 s53, s53, 2
	s_add_u32 s22, s22, 0x100
	s_addc_u32 s23, s23, 0
	s_add_u32 s51, s51, 0x100
	s_addc_u32 s52, s52, 0
	s_cmp_gt_u32 s53, 61
	s_barrier
	s_cbranch_scc0 .LBB0_2542
	s_ashr_i32 s9, s8, 31
	s_lshl_b64 s[8:9], s[8:9], 8
	s_lshl_b32 s3, s2, 8
	v_lshl_add_u64 v[140:141], s[8:9], 0, v[132:133]
	s_ashr_i32 s8, s3, 31
	v_mov_b32_e32 v153, s8
	v_or_b32_e32 v152, s3, v134
	v_lshlrev_b64 v[154:155], 10, v[140:141]
	v_lshl_add_u64 v[156:157], v[154:155], 0, v[152:153]
	v_lshl_add_u64 v[154:155], v[156:157], 1, s[10:11]
	global_load_dwordx4 v[166:169], v[154:155], off
	global_load_dwordx4 v[170:173], v[154:155], off offset:256
	s_mov_b32 s9, 0
	s_mov_b32 s8, 0x8000
	v_lshl_add_u64 v[234:235], v[154:155], 0, s[8:9]
	global_load_dwordx4 v[174:177], v[234:235], off
	global_load_dwordx4 v[178:181], v[234:235], off offset:256
	s_mov_b32 s8, 0x10000
	v_lshl_add_u64 v[234:235], v[154:155], 0, s[8:9]
	global_load_dwordx4 v[182:185], v[234:235], off
	global_load_dwordx4 v[186:189], v[234:235], off offset:256
	s_mov_b32 s8, 0x18000
	v_lshl_add_u64 v[234:235], v[154:155], 0, s[8:9]
	global_load_dwordx4 v[202:205], v[234:235], off
	global_load_dwordx4 v[206:209], v[234:235], off offset:256
	s_mov_b32 s8, 0x40000
	v_lshl_add_u64 v[234:235], v[154:155], 0, s[8:9]
	global_load_dwordx4 v[210:213], v[234:235], off
	global_load_dwordx4 v[214:217], v[234:235], off offset:256
	s_mov_b32 s8, 0x48000
	v_lshl_add_u64 v[234:235], v[154:155], 0, s[8:9]
	global_load_dwordx4 v[218:221], v[234:235], off
	global_load_dwordx4 v[222:225], v[234:235], off offset:256
	s_mov_b32 s8, 0x50000
	v_lshl_add_u64 v[234:235], v[154:155], 0, s[8:9]
	global_load_dwordx4 v[226:229], v[234:235], off
	global_load_dwordx4 v[230:233], v[234:235], off offset:256
	s_mov_b32 s8, 0x58000
	v_lshl_add_u64 v[234:235], v[154:155], 0, s[8:9]
	s_mov_b64 s[8:9], -1
	s_and_b64 vcc, exec, s[0:1]
	s_waitcnt vmcnt(13)
	v_cvt_f32_f16_e32 v164, v166
	v_cvt_f32_f16_sdwa v165, v166 dst_sel:DWORD dst_unused:UNUSED_PAD src0_sel:WORD_1
	v_cvt_f32_f16_e32 v160, v167
	v_cvt_f32_f16_sdwa v161, v167 dst_sel:DWORD dst_unused:UNUSED_PAD src0_sel:WORD_1
	v_pk_add_f32 v[126:127], v[126:127], v[164:165]
	v_cvt_f32_f16_e32 v164, v168
	v_cvt_f32_f16_sdwa v165, v168 dst_sel:DWORD dst_unused:UNUSED_PAD src0_sel:WORD_1
	v_pk_add_f32 v[128:129], v[128:129], v[160:161]
	v_cvt_f32_f16_e32 v160, v169
	v_cvt_f32_f16_sdwa v161, v169 dst_sel:DWORD dst_unused:UNUSED_PAD src0_sel:WORD_1
	v_pk_add_f32 v[122:123], v[122:123], v[164:165]
	v_pk_add_f32 v[124:125], v[124:125], v[160:161]
	s_cbranch_vccz .LBB0_2545
	v_cvt_pk_f16_f32 v163, v124, v125
	v_cvt_pk_f16_f32 v162, v122, v123
	v_cvt_pk_f16_f32 v161, v128, v129
	v_cvt_pk_f16_f32 v160, v126, v127
	global_store_dwordx4 v[154:155], v[160:163], off
	s_mov_b64 s[8:9], 0

;   __device__ __forceinline__ void operator()(const f32x4 (&acc)[2][2][4][2], const g8::Unit& u, int ui, int wr, int wc, int fr, int fq) const {
;     ...
;         for (int bj = 0; bj < 2; ++bj) {
;           const size_t idx = base + 128 * bj;
;           const h16x8 xv = *(const h16x8*)(xb + idx);
;           f32x4 x0 = acc[ai][bj][m][0], x1 = acc[ai][bj][m][1];
; #pragma unroll
;           for (int j = 0; j < 4; ++j) { x0[j] += (float)xv[j]; x1[j] += (float)xv[4 + j]; ss += x0[j] * x0[j] + x1[j] * x1[j]; }
;           if (final_out) {
;             __builtin_nontemporal_store(x0, (f32x4*)(xo + idx));
;             __builtin_nontemporal_store(x1, (f32x4*)(xo + idx + 4));
;           } else {
;             *(h16x8*)(xb + idx) = pack8(x0, x1);
;           }
.LBB0_2547:
	v_lshlrev_b64 v[156:157], 1, v[156:157]
	v_or_b32_e32 v156, 0x100, v156
	v_lshl_add_u64 v[156:157], s[10:11], 0, v[156:157]
	s_nop 0
	v_cndmask_b32_e64 v159, 0, 1, s[0:1]
	s_mov_b64 s[22:23], -1
	v_cmp_ne_u32_e64 s[8:9], 1, v159
	s_andn2_b64 vcc, exec, s[0:1]
	s_waitcnt vmcnt(13)
	v_cvt_f32_f16_e32 v164, v170
	v_cvt_f32_f16_sdwa v165, v170 dst_sel:DWORD dst_unused:UNUSED_PAD src0_sel:WORD_1
	v_cvt_f32_f16_e32 v160, v171
	v_cvt_f32_f16_sdwa v161, v171 dst_sel:DWORD dst_unused:UNUSED_PAD src0_sel:WORD_1
	v_pk_add_f32 v[118:119], v[118:119], v[164:165]
	v_cvt_f32_f16_e32 v164, v172
	v_cvt_f32_f16_sdwa v165, v172 dst_sel:DWORD dst_unused:UNUSED_PAD src0_sel:WORD_1
	v_pk_add_f32 v[120:121], v[120:121], v[160:161]
	v_cvt_f32_f16_e32 v160, v173
	v_cvt_f32_f16_sdwa v161, v173 dst_sel:DWORD dst_unused:UNUSED_PAD src0_sel:WORD_1
	global_load_dwordx4 v[166:169], v[234:235], off
	global_load_dwordx4 v[170:173], v[234:235], off offset:256
	v_pk_add_f32 v[114:115], v[114:115], v[164:165]
	v_pk_add_f32 v[116:117], v[116:117], v[160:161]
	s_cbranch_vccnz .LBB0_2549
	v_cvt_pk_f16_f32 v163, v116, v117
	v_cvt_pk_f16_f32 v162, v114, v115
	v_cvt_pk_f16_f32 v161, v120, v121
	v_cvt_pk_f16_f32 v160, v118, v119
	s_mov_b64 s[22:23], 0
	global_store_dwordx4 v[156:157], v[160:163], off

;   __device__ __forceinline__ void operator()(const f32x4 (&acc)[2][2][4][2], const g8::Unit& u, int ui, int wr, int wc, int fr, int fq) const {
;     ...
;         for (int bj = 0; bj < 2; ++bj) {
;           const size_t idx = base + 128 * bj;
;           const h16x8 xv = *(const h16x8*)(xb + idx);
;           f32x4 x0 = acc[ai][bj][m][0], x1 = acc[ai][bj][m][1];
; #pragma unroll
;           for (int j = 0; j < 4; ++j) { x0[j] += (float)xv[j]; x1[j] += (float)xv[4 + j]; ss += x0[j] * x0[j] + x1[j] * x1[j]; }
;           if (final_out) {
;             __builtin_nontemporal_store(x0, (f32x4*)(xo + idx));
;             __builtin_nontemporal_store(x1, (f32x4*)(xo + idx + 4));
;           } else {
;             *(h16x8*)(xb + idx) = pack8(x0, x1);
;           }
.LBB0_2613:
	s_or_b64 exec, exec, s[24:25]
	s_mov_b64 s[2:3], 0xb0
	s_waitcnt lgkmcnt(0)
	v_lshl_add_u64 v[18:19], v[140:141], 0, s[2:3]
	v_lshlrev_b64 v[20:21], 10, v[18:19]
	v_lshl_add_u64 v[22:23], v[20:21], 0, v[152:153]
	v_lshl_add_u64 v[20:21], v[22:23], 1, s[10:11]
	s_nop 0
	s_mov_b64 s[24:25], -1
	s_and_b64 vcc, exec, s[8:9]
	s_waitcnt vmcnt(12)
	v_cvt_f32_f16_e32 v28, v166
	v_cvt_f32_f16_sdwa v29, v166 dst_sel:DWORD dst_unused:UNUSED_PAD src0_sel:WORD_1
	v_cvt_f32_f16_e32 v24, v167
	v_cvt_f32_f16_sdwa v25, v167 dst_sel:DWORD dst_unused:UNUSED_PAD src0_sel:WORD_1
	v_pk_add_f32 v[14:15], v[14:15], v[28:29]
	v_cvt_f32_f16_e32 v28, v168
	v_cvt_f32_f16_sdwa v29, v168 dst_sel:DWORD dst_unused:UNUSED_PAD src0_sel:WORD_1
	v_pk_add_f32 v[16:17], v[16:17], v[24:25]
	v_cvt_f32_f16_e32 v24, v169
	v_cvt_f32_f16_sdwa v25, v169 dst_sel:DWORD dst_unused:UNUSED_PAD src0_sel:WORD_1
	v_pk_add_f32 v[10:11], v[10:11], v[28:29]
	v_pk_add_f32 v[12:13], v[12:13], v[24:25]
	s_cbranch_vccnz .LBB0_2615
	v_cvt_pk_f16_f32 v27, v12, v13
	v_cvt_pk_f16_f32 v26, v10, v11
	v_cvt_pk_f16_f32 v25, v16, v17
	v_cvt_pk_f16_f32 v24, v14, v15
	s_mov_b64 s[24:25], 0
	global_store_dwordx4 v[20:21], v[24:27], off

;   __device__ __forceinline__ void operator()(const f32x4 (&acc)[2][2][4][2], const g8::Unit& u, int ui, int wr, int wc, int fr, int fq) const {
;     ...
;         for (int bj = 0; bj < 2; ++bj) {
;           const size_t idx = base + 128 * bj;
;           const h16x8 xv = *(const h16x8*)(xb + idx);
;           f32x4 x0 = acc[ai][bj][m][0], x1 = acc[ai][bj][m][1];
; #pragma unroll
;           for (int j = 0; j < 4; ++j) { x0[j] += (float)xv[j]; x1[j] += (float)xv[4 + j]; ss += x0[j] * x0[j] + x1[j] * x1[j]; }
;           if (final_out) {
;             __builtin_nontemporal_store(x0, (f32x4*)(xo + idx));
;             __builtin_nontemporal_store(x1, (f32x4*)(xo + idx + 4));
;           } else {
;             *(h16x8*)(xb + idx) = pack8(x0, x1);
;           }
.LBB0_2617:
	v_lshlrev_b64 v[22:23], 1, v[22:23]
	v_or_b32_e32 v22, 0x100, v22
	v_lshl_add_u64 v[22:23], s[10:11], 0, v[22:23]
	s_nop 0
	s_and_b64 vcc, exec, s[8:9]
	s_mov_b64 s[8:9], -1
	s_waitcnt vmcnt(12)
	v_cvt_f32_f16_e32 v28, v170
	v_cvt_f32_f16_sdwa v29, v170 dst_sel:DWORD dst_unused:UNUSED_PAD src0_sel:WORD_1
	v_cvt_f32_f16_e32 v30, v172
	v_cvt_f32_f16_sdwa v31, v172 dst_sel:DWORD dst_unused:UNUSED_PAD src0_sel:WORD_1
	v_cvt_f32_f16_e32 v24, v171
	v_cvt_f32_f16_sdwa v25, v171 dst_sel:DWORD dst_unused:UNUSED_PAD src0_sel:WORD_1
	v_cvt_f32_f16_e32 v26, v173
	v_cvt_f32_f16_sdwa v27, v173 dst_sel:DWORD dst_unused:UNUSED_PAD src0_sel:WORD_1
	v_pk_add_f32 v[6:7], v[6:7], v[28:29]
	v_pk_add_f32 v[2:3], v[2:3], v[30:31]
	v_pk_add_f32 v[8:9], v[8:9], v[24:25]
	v_pk_add_f32 v[4:5], v[4:5], v[26:27]
	s_cbranch_vccnz .LBB0_2619
	v_cvt_pk_f16_f32 v27, v4, v5
	v_cvt_pk_f16_f32 v26, v2, v3
	v_cvt_pk_f16_f32 v25, v8, v9
	v_cvt_pk_f16_f32 v24, v6, v7
	s_mov_b64 s[8:9], 0
	global_store_dwordx4 v[22:23], v[24:27], off
